# group start stagger with a concave offset distribution (idx*(126-idx)/64 steps of s_sleep 10)
# baseline (speedup 1.0000x reference)
; #define LAS __attribute__((address_space(3)))
; __device__ __forceinline__ bool attn_unit(const Ptrs& P, LAS unsigned char* lds, int unit, int tid, int wave, int lane, bool pre, int nxt) {
;     const int n = unit & 31, kh = (unit >> 5) & 3, b = unit >> 7;
;     const int g = wave & 3, q0 = 64 * (wave >> 2), h = kh * 4 + g, r = lane & 31, hh = lane >> 5;
;     unsigned char* ws = P.ws;
;     bf16_t* Qb = (bf16_t*)(ws + WS_Q) + (size_t)(b * SEQ + n * 128 + q0) * DM + h * 64;
;     const bf16_t* Kg = (const bf16_t*)(ws + WS_K) + (size_t)b * SEQ * KVW + kh * 64; const bf16_t* Vg = (const bf16_t*)(ws + WS_VT) + (size_t)(b * 4 + kh) * 64 * SEQ;
;     const bf16_t* Kcg = (const bf16_t*)(ws + WS_KC) + (size_t)b * CTX * KVW + kh * 64; const bf16_t* Vcg = (const bf16_t*)(ws + WS_VCT) + (size_t)(b * 4 + kh) * 64 * CTX;
;     float mq = fabsf(P.qg[lane]), mk = fabsf(P.kg[lane]);
; #pragma unroll
;     for (int o = 1; o < 64; o <<= 1) { mq = fmaxf(mq, __shfl_xor(mq, o)); mk = fmaxf(mk, __shfl_xor(mk, o)); }
;     const float sink2 = P.sink[h] * LOG2E; const float mshift = fmaxf(64.0f * QSCALE * mq * mk, sink2);
;     bf16x8_t qf[2][4];
; #pragma unroll
;     for (int cb = 0; cb < 2; ++cb)
; #pragma unroll
;         for (int ds = 0; ds < 4; ++ds) qf[cb][ds] = __builtin_nontemporal_load((const bf16x8_t*)(Qb + (size_t)(32 * cb + r) * DM + 16 * ds + 8 * hh));
;     f32x16 o[2][2];
; #pragma unroll
;     for (int db = 0; db < 2; ++db)
; #pragma unroll
;         for (int cb = 0; cb < 2; ++cb)
; #pragma unroll
;             for (int i = 0; i < 16; ++i) o[db][cb][i] = 0.f;
;     float rs[2] = {0.f, 0.f};
;     f32x16 negm;
; #pragma unroll
;     for (int i = 0; i < 16; ++i) negm[i] = -mshift;
; __device__ __forceinline__ void mk_p3(const Ptrs& P, LAS unsigned char* lds, int tid, int wave, int lane, int bx, int G, bool dry) {
;     ...
;         { bool pre = false; for (int u = bx; u < NB * 32 * 4; u += G) pre = attn_unit(P, lds, u, tid, wave, lane, pre, u + G < NB * 32 * 4 ? u + G : -1); }
.LBB9_305:
	s_cmp_lt_i32 s92, 4
	s_cselect_b64 s[2:3], -1, 0
	s_and_b64 s[22:23], s[2:3], s[0:1]
	s_andn2_b64 vcc, exec, s[22:23]
	s_cbranch_vccnz .LBB9_444
	v_writelane_b32 v251, s22, 33
	s_cmpk_gt_i32 s97, 0x1ff
	v_and_b32_e32 v171, 31, v208
	v_writelane_b32 v251, s23, 34
	v_writelane_b32 v251, s80, 35
	v_lshrrev_b32_e32 v184, 5, v170
	s_nop 0
	v_writelane_b32 v251, s81, 36
	v_writelane_b32 v251, s96, 37
	v_writelane_b32 v251, s83, 38
	v_writelane_b32 v251, s97, 39
	s_cbranch_scc1 .LBB9_413
	v_mbcnt_lo_u32_b32 v0, -1, 0
	v_mbcnt_hi_u32_b32 v0, -1, v0
	v_and_b32_e32 v1, 64, v0
	v_add_u32_e32 v1, 64, v1
	v_xor_b32_e32 v2, 1, v0
	v_cmp_lt_i32_e32 vcc, v2, v1
	s_bfe_u32 s0, s40, 0x20006
	v_writelane_b32 v251, s0, 40
	v_cndmask_b32_e32 v2, v0, v2, vcc
	v_lshlrev_b32_e32 v185, 2, v2
	v_xor_b32_e32 v2, 2, v0
	v_cmp_lt_i32_e32 vcc, v2, v1
	s_lshl_b32 s0, s50, 4
	s_and_b32 s33, s0, 0x3fffffc0
	v_cndmask_b32_e32 v2, v0, v2, vcc
	v_lshlrev_b32_e32 v186, 2, v2
	v_xor_b32_e32 v2, 4, v0
	v_cmp_lt_i32_e32 vcc, v2, v1
	s_cmpk_lt_u32 s40, 0x8c0
	s_cselect_b64 s[54:55], -1, 0
	v_cndmask_b32_e32 v2, v0, v2, vcc
	v_lshlrev_b32_e32 v187, 2, v2
	v_xor_b32_e32 v2, 8, v0
	v_cmp_lt_i32_e32 vcc, v2, v1
	s_or_b32 s2, s0, 63
	s_or_b32 s3, s33, 32
	v_cndmask_b32_e32 v2, v0, v2, vcc
	v_lshlrev_b32_e32 v188, 2, v2
	v_xor_b32_e32 v2, 16, v0
	v_cmp_lt_i32_e32 vcc, v2, v1
	v_or_b32_e32 v5, 32, v170
	v_lshlrev_b32_e32 v191, 4, v184
	v_cndmask_b32_e32 v2, v0, v2, vcc
	v_lshlrev_b32_e32 v189, 2, v2
	v_xor_b32_e32 v2, 32, v0
	v_cmp_lt_i32_e32 vcc, v2, v1
	v_mov_b32_e32 v1, 0
	v_mul_u32_u24_e32 v6, 0x110, v5
	v_cndmask_b32_e32 v0, v0, v2, vcc
	v_lshlrev_b32_e32 v190, 2, v0
	v_lshlrev_b32_e32 v0, 2, v184
	v_sub_u32_e32 v0, v171, v0
	v_cmp_lt_i32_e64 s[36:37], 10, v0
	v_cmp_gt_i32_e64 s[0:1], 1, v0
	v_cmp_gt_i32_e64 s[4:5], 2, v0
	v_writelane_b32 v251, s36, 41
	v_cmp_gt_i32_e64 s[6:7], 3, v0
	v_cmp_gt_i32_e64 s[8:9], 4, v0
	v_writelane_b32 v251, s37, 42
	v_cmp_lt_i32_e64 s[36:37], 15, v0
	v_cmp_gt_i32_e64 s[10:11], 9, v0
	v_cmp_gt_i32_e64 s[12:13], 10, v0
	v_writelane_b32 v251, s36, 43
	v_cmp_gt_i32_e64 s[14:15], 11, v0
	v_cmp_gt_i32_e64 s[16:17], 12, v0
	v_writelane_b32 v251, s37, 44
	v_cmp_lt_i32_e64 s[36:37], 16, v0
	v_cmp_gt_i32_e64 s[18:19], 17, v0
	v_cmp_gt_i32_e64 s[20:21], 18, v0
	v_writelane_b32 v251, s36, 45
	v_cmp_gt_i32_e64 s[22:23], 19, v0
	v_cmp_gt_i32_e64 s[24:25], 20, v0
	v_writelane_b32 v251, s37, 46
	v_cmp_lt_i32_e64 s[36:37], 17, v0
	v_cmp_gt_i32_e64 s[26:27], 25, v0
	v_cmp_gt_i32_e64 s[28:29], 26, v0
	v_writelane_b32 v251, s36, 47
	v_cmp_gt_i32_e64 s[30:31], 27, v0
	v_cmp_gt_i32_e64 s[34:35], 28, v0
	v_writelane_b32 v251, s37, 48
	v_cmp_lt_i32_e64 s[36:37], 18, v0
	v_cmp_lt_i32_e64 s[56:57], -1, v0
	v_cmp_lt_i32_e64 s[86:87], 0, v0
	v_writelane_b32 v251, s36, 49
	v_cmp_lt_i32_e64 s[60:61], 1, v0
	v_cmp_lt_i32_e64 s[62:63], 2, v0
	v_writelane_b32 v251, s37, 50
	v_cmp_lt_i32_e64 s[36:37], 23, v0
	v_cmp_lt_i32_e64 s[64:65], 7, v0
	v_cmp_lt_i32_e64 s[66:67], 8, v0
	v_writelane_b32 v251, s36, 51
	v_cmp_lt_i32_e64 s[72:73], 9, v0
	v_lshlrev_b32_e32 v4, 3, v184
	v_writelane_b32 v251, s37, 52
	v_cmp_lt_i32_e64 s[36:37], 24, v0
	v_mul_u32_u24_e32 v3, 0x110, v171
	v_lshlrev_b32_e32 v2, 10, v171
	v_writelane_b32 v251, s36, 53
	s_movk_i32 s52, 0x110
	v_add3_u32 v3, v3, v191, 0
	v_writelane_b32 v251, s37, 54
	v_cmp_lt_i32_e64 s[36:37], 25, v0
	v_lshlrev_b32_e32 v176, 1, v4
	s_mov_b32 s77, 0
	v_writelane_b32 v251, s36, 55
	v_add_u32_e32 v195, 0x4800, v3
	v_add_u32_e32 v198, 0xd400, v3
	v_writelane_b32 v251, s37, 56
	v_cmp_lt_i32_e64 s[36:37], 26, v0
	v_lshlrev_b32_e32 v0, 2, v170
	v_mad_u32_u24 v200, v5, s52, 0
	v_writelane_b32 v251, s36, 57
	v_mad_u32_u24 v201, v171, s52, 0
	s_mov_b64 s[68:69], 0
	v_writelane_b32 v251, s37, 58
	s_add_u32 s36, s90, 0x6200000
	v_writelane_b32 v251, s36, 59
	s_addc_u32 s36, s91, 0
	v_writelane_b32 v251, s36, 60
	s_add_u32 s36, s90, 0x7200000
	v_writelane_b32 v251, s36, 61
	s_addc_u32 s36, s91, 0
	v_writelane_b32 v251, s36, 62
	v_mov_b32_e32 v178, v176
	v_readlane_b32 s36, v251, 16
	s_add_u32 s36, s90, 0x4200000
	v_readlane_b32 s37, v251, 17
	v_readlane_b32 s38, v251, 18
	v_readlane_b32 s39, v251, 19
	v_readlane_b32 s40, v251, 20
	v_readlane_b32 s41, v251, 21
	v_readlane_b32 s42, v251, 22
	v_readlane_b32 s43, v251, 23
	v_readlane_b32 s44, v251, 24
	v_readlane_b32 s45, v251, 25
	v_readlane_b32 s46, v251, 26
	v_readlane_b32 s47, v251, 27
	v_readlane_b32 s48, v251, 28
	v_readlane_b32 s49, v251, 29
	v_readlane_b32 s50, v251, 30
	v_readlane_b32 s51, v251, 31
	v_writelane_b32 v251, s36, 63
	s_addc_u32 s36, s91, 0
	v_writelane_b32 v250, s36, 0
	s_add_u32 s36, s90, 0x6a00000
	v_writelane_b32 v250, s36, 1
	s_addc_u32 s36, s91, 0
	v_writelane_b32 v250, s36, 2
	s_add_u32 s36, s90, 0x7280000
	v_writelane_b32 v250, s36, 3
	s_addc_u32 s36, s91, 0
	v_writelane_b32 v250, s36, 4
	s_add_u32 s36, s90, 0x2000000
	v_writelane_b32 v250, s36, 5
	s_addc_u32 s36, s91, 0
	v_lshl_add_u64 v[172:173], s[40:41], 0, v[0:1]
	v_writelane_b32 v250, s36, 6
	s_add_i32 s40, 0, 0x11800
	s_add_i32 s76, 0, 0x16000
	v_writelane_b32 v250, s40, 7
	v_writelane_b32 v250, s76, 8
	v_writelane_b32 v250, s88, 9
	v_lshl_add_u64 v[174:175], s[42:43], 0, v[0:1]
	v_readlane_b32 s36, v251, 32
	v_writelane_b32 v250, s89, 10
	v_writelane_b32 v250, s90, 11
	v_writelane_b32 v250, s91, 12
	v_add3_u32 v0, v6, v191, 0
	v_mul_u32_u24_e32 v6, 0x90, v171
	v_writelane_b32 v250, s92, 13
	v_lshl_or_b32 v192, s36, 6, v170
	s_movk_i32 s37, 0x90
	v_add3_u32 v196, v6, v191, 0
	v_writelane_b32 v250, s93, 14
	v_add_u32_e32 v193, 0xfffffb80, v192
	v_add_u32_e32 v194, 0x4800, v0
	v_add_u32_e32 v197, 0xd400, v0
	v_add_u32_e32 v199, 0x8c00, v196
	v_mad_u32_u24 v202, v171, s37, 0
	v_mov_b32_e32 v179, v1
	v_lshlrev_b32_e32 v180, 1, v2
	v_mov_b32_e32 v181, v1
	s_mov_b32 s36, 0xf0f0f0f1
	s_movk_i32 s37, 0xffef
	s_movk_i32 s38, 0x490
	s_mov_b32 s39, 0x38e38e39
	v_readlane_b32 s42, v251, 39
	v_writelane_b32 v250, s94, 22
	v_writelane_b32 v250, s94, 23
	v_mov_b32_e32 v254, 0x24008
	ds_read_b32 v254, v254
	s_waitcnt lgkmcnt(0)
	v_readfirstlane_b32 s98, v254
	s_nop 3
	s_cmp_eq_u32 s98, 1
	s_cbranch_scc0 .Lrm_a
	s_cmpk_lg_i32 s94, 0x100
	s_cbranch_scc1 .Lrm_a
	s_and_b32 s98, s42, 7
	s_lshl_b32 s98, s98, 3
	s_bfe_u32 s99, s42, 0x30003
	s_or_b32 s98, s98, s99
	s_and_b32 vcc_lo, s98, 7
	s_lshl_b32 vcc_lo, vcc_lo, 3
	s_lshr_b32 vcc_hi, s98, 3
	s_or_b32 vcc_lo, vcc_lo, vcc_hi
	s_nop 0
	s_sub_u32 vcc_hi, 126, vcc_lo
	s_mul_i32 vcc_lo, vcc_lo, vcc_hi
	s_lshr_b32 vcc_lo, vcc_lo, 6
